# RWKV scan: next-chunk k/v/r fetched with 3 dwordx4 loads per thread and staged through LDS (was 24 two-byte loads)
# speedup vs baseline: 1.0232x; 1.0006x over previous
.LBB0_1594:
	s_or_b64 exec, exec, s[4:5]
	s_load_dword s4, s[0:1], 0x1f8
	v_cmp_lt_i32_e32 vcc, 12, v0
	s_waitcnt lgkmcnt(0)
	s_cmp_lt_i32 s4, 13
	s_cselect_b64 s[4:5], -1, 0
	s_and_b64 s[4:5], s[4:5], vcc
	s_and_saveexec_b64 s[10:11], s[4:5]
	s_cbranch_execz .LBB0_1746
	s_cmpk_gt_i32 s2, 0xff
	s_cbranch_scc1 .LBB0_1691
	s_load_dwordx2 s[16:17], s[0:1], 0x1f0
	s_movk_i32 s6, 0x80
	v_mov_b32_e32 v3, 0x13e80000
	v_mov_b32_e32 v4, 0x13a00000
	v_cmp_gt_u32_e32 vcc, s6, v180
	s_waitcnt lgkmcnt(0)
	s_add_u32 s18, s16, 0x8600000
	s_addc_u32 s19, s17, 0
	s_add_u32 s20, s16, 0xaa00000
	s_addc_u32 s21, s17, 0
	s_add_u32 s22, s16, 0xce00000
	s_addc_u32 s23, s17, 0
	v_and_b32_e32 v154, 63, v180
	s_add_u32 s40, s16, 0x14780000
	v_cndmask_b32_e32 v112, v3, v4, vcc
	v_and_b32_e32 v3, 7, v180
	s_load_dwordx2 s[28:29], s[0:1], 0x98
	s_load_dwordx2 s[30:31], s[0:1], 0xb0
	v_lshrrev_b32_e32 v155, 6, v180
	s_addc_u32 s41, s17, 0
	v_lshrrev_b32_e32 v0, 1, v180
	s_add_i32 s6, 32, 0x6000
	v_lshl_add_u32 v158, v3, 5, 32
	v_cmp_eq_u32_e64 s[8:9], 0, v3
	v_lshlrev_b32_e32 v3, 2, v154
	v_and_b32_e32 v156, 31, v180
	v_and_b32_e32 v2, 32, v0
	v_mov_b32_e32 v4, s6
	v_lshl_or_b32 v3, v155, 8, v3
	v_bfe_u32 v1, v180, 5, 1
	v_or_b32_e32 v157, v2, v156
	v_mov_b32_e32 v113, 0
	v_cndmask_b32_e64 v4, v4, 32, vcc
	v_lshlrev_b32_e32 v2, 2, v2
	v_lshlrev_b32_e32 v5, 2, v156
	v_add_u32_e32 v3, 32, v3
	s_load_dwordx2 s[26:27], s[0:1], 0xe8
	s_load_dwordx4 s[12:15], s[0:1], 0xd8
	v_lshlrev_b32_e32 v0, 3, v1
	v_lshl_add_u64 v[114:115], s[16:17], 0, v[112:113]
	v_add3_u32 v4, v4, v2, v5
	v_lshlrev_b32_e32 v5, 10, v1
	v_lshlrev_b32_e32 v112, 4, v1
	v_and_b32_e32 v1, 0x3f8, v180
	v_add_u32_e32 v162, 0x400, v3
	v_add_u32_e32 v163, 0x800, v3
	v_add_u32_e32 v164, 0xc00, v3
	v_add_u32_e32 v165, 0x1000, v3
	v_add_u32_e32 v166, 0x1400, v3
	v_add_u32_e32 v167, 0x1800, v3
	v_add_u32_e32 v168, 0x1c00, v3
	v_mov_b32_e32 v3, 0x1740000
	v_mov_b32_e32 v6, 0x1700000
	v_lshl_add_u64 v[116:117], v[114:115], 0, v[112:113]
	v_add_u32_e32 v159, 32, v1
	v_lshlrev_b32_e32 v1, 3, v180
	v_cndmask_b32_e32 v112, v3, v6, vcc
	s_waitcnt lgkmcnt(0)
	v_mov_b32_e32 v3, s31
	v_mov_b32_e32 v6, s29
	s_movk_i32 s4, 0x7f
	v_lshl_add_u32 v161, v180, 5, 32
	v_lshl_add_u32 v208, v180, 4, 32
	v_add_u32_e32 v208, 0xe000, v208
	v_lshlrev_b32_e32 v209, 1, v154
	v_lshl_add_u32 v209, v155, 7, v209
	v_add_u32_e32 v209, 0xe020, v209
	v_and_b32_e32 v2, 56, v1
	v_mul_i32_i24_e32 v1, 0xffffffe4, v180
	v_cndmask_b32_e32 v121, v3, v6, vcc
	v_mov_b32_e32 v3, s30
	v_mov_b32_e32 v6, s28
	v_cmp_lt_u32_e64 s[4:5], s4, v180
	s_mov_b32 s25, 0
	v_cmp_eq_u32_e64 s[6:7], 0, v154
	v_lshrrev_b32_e32 v160, 3, v180
	v_lshl_add_u64 v[118:119], s[16:17], 0, v[112:113]
	v_cndmask_b32_e32 v120, v3, v6, vcc
	v_add_u32_e32 v169, 0xa100, v159
	v_add_u32_e32 v170, 0x100, v158
	s_mov_b32 s42, 0x6200000
	v_lshlrev_b32_e32 v122, 1, v0
	v_mov_b32_e32 v123, v113
	v_lshlrev_b32_e32 v124, 1, v2
	v_mov_b32_e32 v125, v113
	s_mov_b32 s43, 0xbf1b4598
	s_movk_i32 s44, 0x9ff
	v_add_u32_e32 v171, v4, v5
	v_add_u32_e32 v172, v161, v1
	s_mov_b32 s45, s2
	s_branch .LBB0_1598

.LBB0_1598:
	s_ashr_i32 s30, s45, 7
	s_bfe_u32 s24, s45, 0x30004
	s_and_b32 s38, s45, 15
	s_cmpk_lt_u32 s45, 0x80
	s_cselect_b64 s[28:29], -1, 0
	s_and_b64 s[34:35], s[28:29], exec
	s_cselect_b32 s31, s42, 0x11600000
	s_cselect_b32 s50, 0, 0xff
	s_cselect_b32 s49, 1, -1
	s_add_u32 s39, s16, s31
	s_addc_u32 s48, s17, 0
	s_lshl_b32 s31, s38, 6
	v_or_b32_e32 v0, s31, v154
	v_lshlrev_b32_e32 v1, 2, v0
	global_load_dword v173, v1, s[12:13]
	global_load_dword v174, v1, s[14:15]
	global_load_dword v175, v1, s[26:27]
	v_or_b32_e32 v1, s31, v157
	v_lshl_or_b32 v2, s30, 10, v1
	v_ashrrev_i32_e32 v3, 31, v2
	s_lshl_b32 s34, s30, 16
	v_lshl_add_u64 v[2:3], v[2:3], 2, v[120:121]
	s_ashr_i32 s35, s34, 31
	global_load_dword v176, v[2:3], off
	v_lshl_add_u64 v[2:3], s[34:35], 1, v[118:119]
	v_lshlrev_b32_e32 v112, 7, v1
	v_lshl_add_u64 v[2:3], v[2:3], 0, v[112:113]
	v_lshl_add_u64 v[2:3], v[2:3], 0, v[122:123]
	v_mov_b32_e32 v1, s50
	global_load_dwordx4 v[16:19], v[2:3], off
	global_load_dwordx4 v[20:23], v[2:3], off offset:32
	global_load_dwordx4 v[24:27], v[2:3], off offset:64
	global_load_dwordx4 v[28:31], v[2:3], off offset:96
	v_mad_i32_i24 v2, s49, v156, v1
	s_mulk_i32 s24, 0x900
	v_ashrrev_i32_e32 v3, 31, v2
	v_lshl_add_u64 v[2:3], v[2:3], 0, s[24:25]
	s_lshl_b32 s34, s30, 6
	v_lshlrev_b64 v[2:3], 8, v[2:3]
	s_ashr_i32 s35, s34, 31
	v_lshl_add_u64 v[2:3], v[114:115], 0, v[2:3]
	s_lshl_b64 s[36:37], s[34:35], 1
	s_lshl_b32 s31, s49, 2
	v_lshl_add_u64 v[2:3], v[2:3], 0, s[36:37]
	v_mov_b32_e32 v8, s31
	v_lshl_add_u64 v[2:3], v[2:3], 0, v[122:123]
	v_mad_i32_i24 v177, s49, v155, v8
	s_barrier
	global_load_dwordx4 v[32:35], v[2:3], off
	global_load_dwordx4 v[36:39], v[2:3], off offset:32
	global_load_dwordx4 v[40:43], v[2:3], off offset:64
	global_load_dwordx4 v[44:47], v[2:3], off offset:96
	s_lshl_b32 s72, s38, 7
	s_add_u32 s74, s20, s72
	s_addc_u32 s75, s21, 0
	v_lshl_add_u64 v[202:203], s[74:75], 0, v[124:125]
	s_add_u32 s74, s22, s72
	s_addc_u32 s75, s23, 0
	v_lshl_add_u64 v[204:205], s[74:75], 0, v[124:125]
	s_add_u32 s74, s18, s72
	s_addc_u32 s75, s19, 0
	v_lshl_add_u64 v[206:207], s[74:75], 0, v[124:125]
	v_mad_i32_i24 v2, s49, v160, v1
	v_ashrrev_i32_e32 v3, 31, v2
	v_lshl_add_u64 v[2:3], v[2:3], 0, s[24:25]
	v_lshlrev_b64 v[2:3], 11, v[2:3]
	v_lshl_add_u64 v[4:5], v[202:203], 0, v[2:3]
	v_lshl_add_u64 v[6:7], v[204:205], 0, v[2:3]
	v_lshl_add_u64 v[8:9], v[206:207], 0, v[2:3]
	global_load_dwordx4 v[184:187], v[4:5], off
	global_load_dwordx4 v[188:191], v[6:7], off
	global_load_dwordx4 v[198:201], v[8:9], off
	v_lshlrev_b32_e32 v1, 1, v0
	s_mul_hi_i32 s31, s30, 0x4800
	s_mulk_i32 s30, 0x4800
	s_add_u32 s30, s30, s24
	s_addc_u32 s31, s31, 0
	s_lshl_b32 s34, s38, 2
	s_add_u32 s34, s40, s34
	s_addc_u32 s35, s41, 0
	v_lshl_add_u64 v[126:127], v[116:117], 0, s[36:37]
	s_lshl_b32 s36, s38, 7
	s_add_u32 s36, s39, s36
	s_addc_u32 s37, s48, 0
	v_mov_b32_e32 v112, v113
	v_mul_i32_i24_e32 v194, s49, v156
	v_mul_i32_i24_e32 v195, s49, v155
	v_mul_i32_i24_e32 v196, s49, v160
	v_lshl_add_u64 v[128:129], s[36:37], 0, v[124:125]
	v_lshlrev_b32_e32 v197, 1, v0
	v_mov_b64_e32 v[130:131], v[112:113]
	v_mov_b64_e32 v[132:133], v[112:113]
	v_mov_b64_e32 v[134:135], v[112:113]
	v_mov_b64_e32 v[136:137], v[112:113]
	v_mov_b64_e32 v[138:139], v[112:113]
	v_mov_b64_e32 v[140:141], v[112:113]
	v_mov_b64_e32 v[142:143], v[112:113]
	v_mov_b64_e32 v[144:145], v[112:113]
	s_mov_b32 s48, s25
	s_branch .LBB0_1600

.LBB0_1600:
	s_waitcnt vmcnt(6)
	v_mfma_f32_32x32x16_bf16 v[0:15], v[32:35], v[16:19], 0
	s_waitcnt vmcnt(5)
	v_mfma_f32_32x32x16_bf16 v[0:15], v[36:39], v[20:23], v[0:15]
	s_waitcnt vmcnt(4)
	v_mfma_f32_32x32x16_bf16 v[0:15], v[40:43], v[24:27], v[0:15]
	s_waitcnt vmcnt(3)
	v_mfma_f32_32x32x16_bf16 v[0:15], v[44:47], v[28:31], v[0:15]
	s_waitcnt vmcnt(0)
	ds_write_b128 v208, v[184:187]
	ds_write_b128 v208, v[188:191] offset:4096
	ds_write_b128 v208, v[198:201] offset:8192
	s_nop 7
	s_and_b64 vcc, exec, s[4:5]
	s_cbranch_vccz .Lrw_p1_decay
	v_add_f32_e32 v48, v176, v0
	v_add_f32_e32 v49, v176, v1
	v_max_f32_e32 v48, 0xc2a00000, v48
	v_max_f32_e32 v49, 0xc2a00000, v49
	v_mul_f32_e32 v48, 0xbfb8aa3b, v48
	v_mul_f32_e32 v49, 0xbfb8aa3b, v49
	v_exp_f32_e32 v48, v48
	v_exp_f32_e32 v49, v49
	v_add_f32_e32 v50, 1.0, v48
	v_add_f32_e32 v51, 1.0, v49
	v_rcp_f32_e32 v52, v50
	v_rcp_f32_e32 v53, v51
	v_fma_f32 v54, -v50, v52, 1.0
	v_fma_f32 v55, -v51, v53, 1.0
	v_fma_f32 v52, v52, v54, v52
	v_fma_f32 v53, v53, v55, v53
	ds_write_b32 v171, v52
	ds_write_b32 v171, v53 offset:256
	v_add_f32_e32 v48, v176, v2
	v_add_f32_e32 v49, v176, v3
	v_max_f32_e32 v48, 0xc2a00000, v48
	v_max_f32_e32 v49, 0xc2a00000, v49
	v_mul_f32_e32 v48, 0xbfb8aa3b, v48
	v_mul_f32_e32 v49, 0xbfb8aa3b, v49
	v_exp_f32_e32 v48, v48
	v_exp_f32_e32 v49, v49
	v_add_f32_e32 v50, 1.0, v48
	v_add_f32_e32 v51, 1.0, v49
	v_rcp_f32_e32 v52, v50
	v_rcp_f32_e32 v53, v51
	v_fma_f32 v54, -v50, v52, 1.0
	v_fma_f32 v55, -v51, v53, 1.0
	v_fma_f32 v52, v52, v54, v52
	v_fma_f32 v53, v53, v55, v53
	ds_write_b32 v171, v52 offset:512
	ds_write_b32 v171, v53 offset:768
	v_add_f32_e32 v48, v176, v4
	v_add_f32_e32 v49, v176, v5
	v_max_f32_e32 v48, 0xc2a00000, v48
	v_max_f32_e32 v49, 0xc2a00000, v49
	v_mul_f32_e32 v48, 0xbfb8aa3b, v48
	v_mul_f32_e32 v49, 0xbfb8aa3b, v49
	v_exp_f32_e32 v48, v48
	v_exp_f32_e32 v49, v49
	v_add_f32_e32 v50, 1.0, v48
	v_add_f32_e32 v51, 1.0, v49
	v_rcp_f32_e32 v52, v50
	v_rcp_f32_e32 v53, v51
	v_fma_f32 v54, -v50, v52, 1.0
	v_fma_f32 v55, -v51, v53, 1.0
	v_fma_f32 v52, v52, v54, v52
	v_fma_f32 v53, v53, v55, v53
	ds_write_b32 v171, v52 offset:2048
	ds_write_b32 v171, v53 offset:2304
	v_add_f32_e32 v48, v176, v6
	v_add_f32_e32 v49, v176, v7
	v_max_f32_e32 v48, 0xc2a00000, v48
	v_max_f32_e32 v49, 0xc2a00000, v49
	v_mul_f32_e32 v48, 0xbfb8aa3b, v48
	v_mul_f32_e32 v49, 0xbfb8aa3b, v49
	v_exp_f32_e32 v48, v48
	v_exp_f32_e32 v49, v49
	v_add_f32_e32 v50, 1.0, v48
	v_add_f32_e32 v51, 1.0, v49
	v_rcp_f32_e32 v52, v50
	v_rcp_f32_e32 v53, v51
	v_fma_f32 v54, -v50, v52, 1.0
	v_fma_f32 v55, -v51, v53, 1.0
	v_fma_f32 v52, v52, v54, v52
	v_fma_f32 v53, v53, v55, v53
	ds_write_b32 v171, v52 offset:2560
	ds_write_b32 v171, v53 offset:2816
	v_add_f32_e32 v48, v176, v8
	v_add_f32_e32 v49, v176, v9
	v_max_f32_e32 v48, 0xc2a00000, v48
	v_max_f32_e32 v49, 0xc2a00000, v49
	v_mul_f32_e32 v48, 0xbfb8aa3b, v48
	v_mul_f32_e32 v49, 0xbfb8aa3b, v49
	v_exp_f32_e32 v48, v48
	v_exp_f32_e32 v49, v49
	v_add_f32_e32 v50, 1.0, v48
	v_add_f32_e32 v51, 1.0, v49
	v_rcp_f32_e32 v52, v50
	v_rcp_f32_e32 v53, v51
	v_fma_f32 v54, -v50, v52, 1.0
	v_fma_f32 v55, -v51, v53, 1.0
	v_fma_f32 v52, v52, v54, v52
	v_fma_f32 v53, v53, v55, v53
	ds_write_b32 v171, v52 offset:4096
	ds_write_b32 v171, v53 offset:4352
	v_add_f32_e32 v48, v176, v10
	v_add_f32_e32 v49, v176, v11
	v_max_f32_e32 v48, 0xc2a00000, v48
	v_max_f32_e32 v49, 0xc2a00000, v49
	v_mul_f32_e32 v48, 0xbfb8aa3b, v48
	v_mul_f32_e32 v49, 0xbfb8aa3b, v49
	v_exp_f32_e32 v48, v48
	v_exp_f32_e32 v49, v49
	v_add_f32_e32 v50, 1.0, v48
	v_add_f32_e32 v51, 1.0, v49
	v_rcp_f32_e32 v52, v50
	v_rcp_f32_e32 v53, v51
	v_fma_f32 v54, -v50, v52, 1.0
	v_fma_f32 v55, -v51, v53, 1.0
	v_fma_f32 v52, v52, v54, v52
	v_fma_f32 v53, v53, v55, v53
	ds_write_b32 v171, v52 offset:4608
	ds_write_b32 v171, v53 offset:4864
	v_add_f32_e32 v48, v176, v12
	v_add_f32_e32 v49, v176, v13
	v_max_f32_e32 v48, 0xc2a00000, v48
	v_max_f32_e32 v49, 0xc2a00000, v49
	v_mul_f32_e32 v48, 0xbfb8aa3b, v48
	v_mul_f32_e32 v49, 0xbfb8aa3b, v49
	v_exp_f32_e32 v48, v48
	v_exp_f32_e32 v49, v49
	v_add_f32_e32 v50, 1.0, v48
	v_add_f32_e32 v51, 1.0, v49
	v_rcp_f32_e32 v52, v50
	v_rcp_f32_e32 v53, v51
	v_fma_f32 v54, -v50, v52, 1.0
	v_fma_f32 v55, -v51, v53, 1.0
	v_fma_f32 v52, v52, v54, v52
	v_fma_f32 v53, v53, v55, v53
	ds_write_b32 v171, v52 offset:6144
	ds_write_b32 v171, v53 offset:6400
	v_add_f32_e32 v48, v176, v14
	v_add_f32_e32 v49, v176, v15
	v_max_f32_e32 v48, 0xc2a00000, v48
	v_max_f32_e32 v49, 0xc2a00000, v49
	v_mul_f32_e32 v48, 0xbfb8aa3b, v48
	v_mul_f32_e32 v49, 0xbfb8aa3b, v49
	v_exp_f32_e32 v48, v48
	v_exp_f32_e32 v49, v49
	v_add_f32_e32 v50, 1.0, v48
	v_add_f32_e32 v51, 1.0, v49
	v_rcp_f32_e32 v52, v50
	v_rcp_f32_e32 v53, v51
	v_fma_f32 v54, -v50, v52, 1.0
	v_fma_f32 v55, -v51, v53, 1.0
	v_fma_f32 v52, v52, v54, v52
	v_fma_f32 v53, v53, v55, v53
	ds_write_b32 v171, v52 offset:6656
	ds_write_b32 v171, v53 offset:6912
	s_branch .Lrw_p1_done

.Lrw_p1_done:
	s_waitcnt lgkmcnt(0)
	s_barrier
	s_lshl_b32 s38, s48, 5
	s_cmp_lt_u32 s48, 8
	s_cselect_b32 s36, 0xff, s44
	s_sub_i32 s39, s36, s38
	s_and_b64 s[36:37], s[28:29], exec
	s_cselect_b32 s49, s38, s39
	ds_read_b32 v48, v172 offset:24576
	ds_read_b32 v49, v162 offset:24576
	ds_read_b32 v50, v163 offset:24576
	ds_read_b32 v51, v164 offset:24576
	ds_read_b32 v52, v165 offset:24576
	ds_read_b32 v53, v166 offset:24576
	ds_read_b32 v54, v167 offset:24576
	ds_read_b32 v55, v168 offset:24576
	ds_read_u16 v56, v209 offset:0
	ds_read_u16 v32, v209 offset:4096
	ds_read_u16 v64, v209 offset:8192
	ds_read_u16 v57, v209 offset:512
	ds_read_u16 v33, v209 offset:4608
	ds_read_u16 v65, v209 offset:8704
	ds_read_u16 v58, v209 offset:1024
	ds_read_u16 v34, v209 offset:5120
	ds_read_u16 v66, v209 offset:9216
	ds_read_u16 v59, v209 offset:1536
	ds_read_u16 v35, v209 offset:5632
	ds_read_u16 v67, v209 offset:9728
	ds_read_u16 v60, v209 offset:2048
	ds_read_u16 v36, v209 offset:6144
	ds_read_u16 v68, v209 offset:10240
	ds_read_u16 v61, v209 offset:2560
	ds_read_u16 v37, v209 offset:6656
	ds_read_u16 v69, v209 offset:10752
	ds_read_u16 v62, v209 offset:3072
	ds_read_u16 v38, v209 offset:7168
	ds_read_u16 v70, v209 offset:11264
	ds_read_u16 v63, v209 offset:3584
	ds_read_u16 v39, v209 offset:7680
	ds_read_u16 v71, v209 offset:11776
	s_waitcnt vmcnt(0) lgkmcnt(0)
	v_lshlrev_b32_e32 v56, 16, v56
	v_lshlrev_b32_e32 v57, 16, v57
	v_lshlrev_b32_e32 v64, 16, v64
	v_lshlrev_b32_e32 v65, 16, v65
	v_add_f32_e32 v104, -1.0, v48
	v_add_f32_e32 v105, -1.0, v49
	v_fma_f32 v72, v174, v104, 1.0
	v_fma_f32 v73, v174, v105, 1.0
	v_mul_f32_e32 v80, v173, v56
	v_mul_f32_e32 v81, v173, v57
	v_mul_f32_e32 v72, v72, v56
	v_mul_f32_e32 v73, v73, v57
	v_mul_f32_e32 v88, v80, v80
	v_mul_f32_e32 v89, v81, v81
	v_mul_f32_e32 v96, v72, v64
	v_mul_f32_e32 v97, v73, v65
	v_mul_f32_e32 v96, v175, v96
	v_mul_f32_e32 v97, v175, v97
	v_add_f32_dpp v88, v88, v88 quad_perm:[1,0,3,2] row_mask:0xf bank_mask:0xf bound_ctrl:1
	v_add_f32_dpp v96, v96, v96 quad_perm:[1,0,3,2] row_mask:0xf bank_mask:0xf bound_ctrl:1
	v_add_f32_dpp v89, v89, v89 quad_perm:[1,0,3,2] row_mask:0xf bank_mask:0xf bound_ctrl:1
	v_add_f32_dpp v97, v97, v97 quad_perm:[1,0,3,2] row_mask:0xf bank_mask:0xf bound_ctrl:1
	v_add_f32_dpp v88, v88, v88 quad_perm:[2,3,0,1] row_mask:0xf bank_mask:0xf bound_ctrl:1
	v_add_f32_dpp v96, v96, v96 quad_perm:[2,3,0,1] row_mask:0xf bank_mask:0xf bound_ctrl:1
	v_add_f32_dpp v89, v89, v89 quad_perm:[2,3,0,1] row_mask:0xf bank_mask:0xf bound_ctrl:1
	v_add_f32_dpp v97, v97, v97 quad_perm:[2,3,0,1] row_mask:0xf bank_mask:0xf bound_ctrl:1
	v_add_f32_dpp v88, v88, v88 row_half_mirror row_mask:0xf bank_mask:0xf bound_ctrl:1
	v_add_f32_dpp v96, v96, v96 row_half_mirror row_mask:0xf bank_mask:0xf bound_ctrl:1
	v_add_f32_dpp v89, v89, v89 row_half_mirror row_mask:0xf bank_mask:0xf bound_ctrl:1
	v_add_f32_dpp v97, v97, v97 row_half_mirror row_mask:0xf bank_mask:0xf bound_ctrl:1
	v_add_f32_dpp v88, v88, v88 row_mirror row_mask:0xf bank_mask:0xf bound_ctrl:1
	v_add_f32_dpp v96, v96, v96 row_mirror row_mask:0xf bank_mask:0xf bound_ctrl:1
	v_add_f32_dpp v89, v89, v89 row_mirror row_mask:0xf bank_mask:0xf bound_ctrl:1
	v_add_f32_dpp v97, v97, v97 row_mirror row_mask:0xf bank_mask:0xf bound_ctrl:1
	v_add_f32_dpp v88, v88, v88 row_bcast:15 row_mask:0xa bank_mask:0xf
	v_add_f32_dpp v96, v96, v96 row_bcast:15 row_mask:0xa bank_mask:0xf
	v_add_f32_dpp v89, v89, v89 row_bcast:15 row_mask:0xa bank_mask:0xf
	v_add_f32_dpp v97, v97, v97 row_bcast:15 row_mask:0xa bank_mask:0xf
	v_add_f32_dpp v88, v88, v88 row_bcast:31 row_mask:0xc bank_mask:0xf
	v_add_f32_dpp v96, v96, v96 row_bcast:31 row_mask:0xc bank_mask:0xf
	v_add_f32_dpp v89, v89, v89 row_bcast:31 row_mask:0xc bank_mask:0xf
	v_add_f32_dpp v97, v97, v97 row_bcast:31 row_mask:0xc bank_mask:0xf
	v_readlane_b32 s50, v88, 63
	v_readlane_b32 s51, v89, 63
	v_readlane_b32 s64, v96, 63
	v_readlane_b32 s65, v97, 63
	s_max_u32 s50, s50, 0x179abe15
	s_max_u32 s51, s51, 0x179abe15
	v_rsq_f32_e32 v104, s50
	v_rsq_f32_e32 v105, s51
	v_lshlrev_b32_e32 v88, 16, v32
	v_lshlrev_b32_e32 v89, 16, v33
	v_mul_f32_e64 v80, v80, -v104
	v_mul_f32_e64 v81, v81, -v105
	v_mul_f32_e64 v96, v48, -v80
	v_mul_f32_e64 v97, v49, -v81
	ds_write2st64_b32 v172, v72, v80 offset0:32 offset1:64
	ds_write2st64_b32 v172, v96, v64 offset0:96 offset1:128
	ds_write_b32 v172, v88 offset:40960
	ds_write2st64_b32 v162, v73, v81 offset0:32 offset1:64
	ds_write2st64_b32 v162, v97, v65 offset0:96 offset1:128
	ds_write_b32 v162, v89 offset:40960
	v_lshlrev_b32_e32 v58, 16, v58
	v_lshlrev_b32_e32 v59, 16, v59
	v_lshlrev_b32_e32 v66, 16, v66
	v_lshlrev_b32_e32 v67, 16, v67
	v_add_f32_e32 v106, -1.0, v50
	v_add_f32_e32 v107, -1.0, v51
	v_fma_f32 v74, v174, v106, 1.0
	v_fma_f32 v75, v174, v107, 1.0
	v_mul_f32_e32 v82, v173, v58
	v_mul_f32_e32 v83, v173, v59
	v_mul_f32_e32 v74, v74, v58
	v_mul_f32_e32 v75, v75, v59
	v_mul_f32_e32 v90, v82, v82
	v_mul_f32_e32 v91, v83, v83
	v_mul_f32_e32 v98, v74, v66
	v_mul_f32_e32 v99, v75, v67
	v_mul_f32_e32 v98, v175, v98
	v_mul_f32_e32 v99, v175, v99
	v_add_f32_dpp v90, v90, v90 quad_perm:[1,0,3,2] row_mask:0xf bank_mask:0xf bound_ctrl:1
	v_add_f32_dpp v98, v98, v98 quad_perm:[1,0,3,2] row_mask:0xf bank_mask:0xf bound_ctrl:1
	v_add_f32_dpp v91, v91, v91 quad_perm:[1,0,3,2] row_mask:0xf bank_mask:0xf bound_ctrl:1
	v_add_f32_dpp v99, v99, v99 quad_perm:[1,0,3,2] row_mask:0xf bank_mask:0xf bound_ctrl:1
	v_add_f32_dpp v90, v90, v90 quad_perm:[2,3,0,1] row_mask:0xf bank_mask:0xf bound_ctrl:1
	v_add_f32_dpp v98, v98, v98 quad_perm:[2,3,0,1] row_mask:0xf bank_mask:0xf bound_ctrl:1
	v_add_f32_dpp v91, v91, v91 quad_perm:[2,3,0,1] row_mask:0xf bank_mask:0xf bound_ctrl:1
	v_add_f32_dpp v99, v99, v99 quad_perm:[2,3,0,1] row_mask:0xf bank_mask:0xf bound_ctrl:1
	v_add_f32_dpp v90, v90, v90 row_half_mirror row_mask:0xf bank_mask:0xf bound_ctrl:1
	v_add_f32_dpp v98, v98, v98 row_half_mirror row_mask:0xf bank_mask:0xf bound_ctrl:1
	v_add_f32_dpp v91, v91, v91 row_half_mirror row_mask:0xf bank_mask:0xf bound_ctrl:1
	v_add_f32_dpp v99, v99, v99 row_half_mirror row_mask:0xf bank_mask:0xf bound_ctrl:1
	v_add_f32_dpp v90, v90, v90 row_mirror row_mask:0xf bank_mask:0xf bound_ctrl:1
	v_add_f32_dpp v98, v98, v98 row_mirror row_mask:0xf bank_mask:0xf bound_ctrl:1
	v_add_f32_dpp v91, v91, v91 row_mirror row_mask:0xf bank_mask:0xf bound_ctrl:1
	v_add_f32_dpp v99, v99, v99 row_mirror row_mask:0xf bank_mask:0xf bound_ctrl:1
	v_add_f32_dpp v90, v90, v90 row_bcast:15 row_mask:0xa bank_mask:0xf
	v_add_f32_dpp v98, v98, v98 row_bcast:15 row_mask:0xa bank_mask:0xf
	v_add_f32_dpp v91, v91, v91 row_bcast:15 row_mask:0xa bank_mask:0xf
	v_add_f32_dpp v99, v99, v99 row_bcast:15 row_mask:0xa bank_mask:0xf
	v_add_f32_dpp v90, v90, v90 row_bcast:31 row_mask:0xc bank_mask:0xf
	v_add_f32_dpp v98, v98, v98 row_bcast:31 row_mask:0xc bank_mask:0xf
	v_add_f32_dpp v91, v91, v91 row_bcast:31 row_mask:0xc bank_mask:0xf
	v_add_f32_dpp v99, v99, v99 row_bcast:31 row_mask:0xc bank_mask:0xf
	v_readlane_b32 s50, v90, 63
	v_readlane_b32 s51, v91, 63
	v_readlane_b32 s66, v98, 63
	v_readlane_b32 s67, v99, 63
	s_max_u32 s50, s50, 0x179abe15
	s_max_u32 s51, s51, 0x179abe15
	v_rsq_f32_e32 v106, s50
	v_rsq_f32_e32 v107, s51
	v_lshlrev_b32_e32 v90, 16, v34
	v_lshlrev_b32_e32 v91, 16, v35
	v_mul_f32_e64 v82, v82, -v106
	v_mul_f32_e64 v83, v83, -v107
	v_mul_f32_e64 v98, v50, -v82
	v_mul_f32_e64 v99, v51, -v83
	ds_write2st64_b32 v163, v74, v82 offset0:32 offset1:64
	ds_write2st64_b32 v163, v98, v66 offset0:96 offset1:128
	ds_write_b32 v163, v90 offset:40960
	ds_write2st64_b32 v164, v75, v83 offset0:32 offset1:64
	ds_write2st64_b32 v164, v99, v67 offset0:96 offset1:128
	ds_write_b32 v164, v91 offset:40960
	v_lshlrev_b32_e32 v60, 16, v60
	v_lshlrev_b32_e32 v61, 16, v61
	v_lshlrev_b32_e32 v68, 16, v68
	v_lshlrev_b32_e32 v69, 16, v69
	v_add_f32_e32 v108, -1.0, v52
	v_add_f32_e32 v109, -1.0, v53
	v_fma_f32 v76, v174, v108, 1.0
	v_fma_f32 v77, v174, v109, 1.0
	v_mul_f32_e32 v84, v173, v60
	v_mul_f32_e32 v85, v173, v61
	v_mul_f32_e32 v76, v76, v60
	v_mul_f32_e32 v77, v77, v61
	v_mul_f32_e32 v92, v84, v84
	v_mul_f32_e32 v93, v85, v85
	v_mul_f32_e32 v100, v76, v68
	v_mul_f32_e32 v101, v77, v69
	v_mul_f32_e32 v100, v175, v100
	v_mul_f32_e32 v101, v175, v101
	v_add_f32_dpp v92, v92, v92 quad_perm:[1,0,3,2] row_mask:0xf bank_mask:0xf bound_ctrl:1
	v_add_f32_dpp v100, v100, v100 quad_perm:[1,0,3,2] row_mask:0xf bank_mask:0xf bound_ctrl:1
	v_add_f32_dpp v93, v93, v93 quad_perm:[1,0,3,2] row_mask:0xf bank_mask:0xf bound_ctrl:1
	v_add_f32_dpp v101, v101, v101 quad_perm:[1,0,3,2] row_mask:0xf bank_mask:0xf bound_ctrl:1
	v_add_f32_dpp v92, v92, v92 quad_perm:[2,3,0,1] row_mask:0xf bank_mask:0xf bound_ctrl:1
	v_add_f32_dpp v100, v100, v100 quad_perm:[2,3,0,1] row_mask:0xf bank_mask:0xf bound_ctrl:1
	v_add_f32_dpp v93, v93, v93 quad_perm:[2,3,0,1] row_mask:0xf bank_mask:0xf bound_ctrl:1
	v_add_f32_dpp v101, v101, v101 quad_perm:[2,3,0,1] row_mask:0xf bank_mask:0xf bound_ctrl:1
	v_add_f32_dpp v92, v92, v92 row_half_mirror row_mask:0xf bank_mask:0xf bound_ctrl:1
	v_add_f32_dpp v100, v100, v100 row_half_mirror row_mask:0xf bank_mask:0xf bound_ctrl:1
	v_add_f32_dpp v93, v93, v93 row_half_mirror row_mask:0xf bank_mask:0xf bound_ctrl:1
	v_add_f32_dpp v101, v101, v101 row_half_mirror row_mask:0xf bank_mask:0xf bound_ctrl:1
	v_add_f32_dpp v92, v92, v92 row_mirror row_mask:0xf bank_mask:0xf bound_ctrl:1
	v_add_f32_dpp v100, v100, v100 row_mirror row_mask:0xf bank_mask:0xf bound_ctrl:1
	v_add_f32_dpp v93, v93, v93 row_mirror row_mask:0xf bank_mask:0xf bound_ctrl:1
	v_add_f32_dpp v101, v101, v101 row_mirror row_mask:0xf bank_mask:0xf bound_ctrl:1
	v_add_f32_dpp v92, v92, v92 row_bcast:15 row_mask:0xa bank_mask:0xf
	v_add_f32_dpp v100, v100, v100 row_bcast:15 row_mask:0xa bank_mask:0xf
	v_add_f32_dpp v93, v93, v93 row_bcast:15 row_mask:0xa bank_mask:0xf
	v_add_f32_dpp v101, v101, v101 row_bcast:15 row_mask:0xa bank_mask:0xf
	v_add_f32_dpp v92, v92, v92 row_bcast:31 row_mask:0xc bank_mask:0xf
	v_add_f32_dpp v100, v100, v100 row_bcast:31 row_mask:0xc bank_mask:0xf
	v_add_f32_dpp v93, v93, v93 row_bcast:31 row_mask:0xc bank_mask:0xf
	v_add_f32_dpp v101, v101, v101 row_bcast:31 row_mask:0xc bank_mask:0xf
	v_readlane_b32 s50, v92, 63
	v_readlane_b32 s51, v93, 63
	v_readlane_b32 s68, v100, 63
	v_readlane_b32 s69, v101, 63
	s_max_u32 s50, s50, 0x179abe15
	s_max_u32 s51, s51, 0x179abe15
	v_rsq_f32_e32 v108, s50
	v_rsq_f32_e32 v109, s51
	v_lshlrev_b32_e32 v92, 16, v36
	v_lshlrev_b32_e32 v93, 16, v37
	v_mul_f32_e64 v84, v84, -v108
	v_mul_f32_e64 v85, v85, -v109
	v_mul_f32_e64 v100, v52, -v84
	v_mul_f32_e64 v101, v53, -v85
	ds_write2st64_b32 v165, v76, v84 offset0:32 offset1:64
	ds_write2st64_b32 v165, v100, v68 offset0:96 offset1:128
	ds_write_b32 v165, v92 offset:40960
	ds_write2st64_b32 v166, v77, v85 offset0:32 offset1:64
	ds_write2st64_b32 v166, v101, v69 offset0:96 offset1:128
	ds_write_b32 v166, v93 offset:40960
	v_lshlrev_b32_e32 v62, 16, v62
	v_lshlrev_b32_e32 v63, 16, v63
	v_lshlrev_b32_e32 v70, 16, v70
	v_lshlrev_b32_e32 v71, 16, v71
	v_add_f32_e32 v110, -1.0, v54
	v_add_f32_e32 v111, -1.0, v55
	v_fma_f32 v78, v174, v110, 1.0
	v_fma_f32 v79, v174, v111, 1.0
	v_mul_f32_e32 v86, v173, v62
	v_mul_f32_e32 v87, v173, v63
	v_mul_f32_e32 v78, v78, v62
	v_mul_f32_e32 v79, v79, v63
	v_mul_f32_e32 v94, v86, v86
	v_mul_f32_e32 v95, v87, v87
	v_mul_f32_e32 v102, v78, v70
	v_mul_f32_e32 v103, v79, v71
	v_mul_f32_e32 v102, v175, v102
	v_mul_f32_e32 v103, v175, v103
	v_add_f32_dpp v94, v94, v94 quad_perm:[1,0,3,2] row_mask:0xf bank_mask:0xf bound_ctrl:1
	v_add_f32_dpp v102, v102, v102 quad_perm:[1,0,3,2] row_mask:0xf bank_mask:0xf bound_ctrl:1
	v_add_f32_dpp v95, v95, v95 quad_perm:[1,0,3,2] row_mask:0xf bank_mask:0xf bound_ctrl:1
	v_add_f32_dpp v103, v103, v103 quad_perm:[1,0,3,2] row_mask:0xf bank_mask:0xf bound_ctrl:1
	v_add_f32_dpp v94, v94, v94 quad_perm:[2,3,0,1] row_mask:0xf bank_mask:0xf bound_ctrl:1
	v_add_f32_dpp v102, v102, v102 quad_perm:[2,3,0,1] row_mask:0xf bank_mask:0xf bound_ctrl:1
	v_add_f32_dpp v95, v95, v95 quad_perm:[2,3,0,1] row_mask:0xf bank_mask:0xf bound_ctrl:1
	v_add_f32_dpp v103, v103, v103 quad_perm:[2,3,0,1] row_mask:0xf bank_mask:0xf bound_ctrl:1
	v_add_f32_dpp v94, v94, v94 row_half_mirror row_mask:0xf bank_mask:0xf bound_ctrl:1
	v_add_f32_dpp v102, v102, v102 row_half_mirror row_mask:0xf bank_mask:0xf bound_ctrl:1
	v_add_f32_dpp v95, v95, v95 row_half_mirror row_mask:0xf bank_mask:0xf bound_ctrl:1
	v_add_f32_dpp v103, v103, v103 row_half_mirror row_mask:0xf bank_mask:0xf bound_ctrl:1
	v_add_f32_dpp v94, v94, v94 row_mirror row_mask:0xf bank_mask:0xf bound_ctrl:1
	v_add_f32_dpp v102, v102, v102 row_mirror row_mask:0xf bank_mask:0xf bound_ctrl:1
	v_add_f32_dpp v95, v95, v95 row_mirror row_mask:0xf bank_mask:0xf bound_ctrl:1
	v_add_f32_dpp v103, v103, v103 row_mirror row_mask:0xf bank_mask:0xf bound_ctrl:1
	v_add_f32_dpp v94, v94, v94 row_bcast:15 row_mask:0xa bank_mask:0xf
	v_add_f32_dpp v102, v102, v102 row_bcast:15 row_mask:0xa bank_mask:0xf
	v_add_f32_dpp v95, v95, v95 row_bcast:15 row_mask:0xa bank_mask:0xf
	v_add_f32_dpp v103, v103, v103 row_bcast:15 row_mask:0xa bank_mask:0xf
	v_add_f32_dpp v94, v94, v94 row_bcast:31 row_mask:0xc bank_mask:0xf
	v_add_f32_dpp v102, v102, v102 row_bcast:31 row_mask:0xc bank_mask:0xf
	v_add_f32_dpp v95, v95, v95 row_bcast:31 row_mask:0xc bank_mask:0xf
	v_add_f32_dpp v103, v103, v103 row_bcast:31 row_mask:0xc bank_mask:0xf
	v_readlane_b32 s50, v94, 63
	v_readlane_b32 s51, v95, 63
	v_readlane_b32 s70, v102, 63
	v_readlane_b32 s71, v103, 63
	s_max_u32 s50, s50, 0x179abe15
	s_max_u32 s51, s51, 0x179abe15
	v_rsq_f32_e32 v110, s50
	v_rsq_f32_e32 v111, s51
	v_lshlrev_b32_e32 v94, 16, v38
	v_lshlrev_b32_e32 v95, 16, v39
	v_mul_f32_e64 v86, v86, -v110
	v_mul_f32_e64 v87, v87, -v111
	v_mul_f32_e64 v102, v54, -v86
	v_mul_f32_e64 v103, v55, -v87
	ds_write2st64_b32 v167, v78, v86 offset0:32 offset1:64
	ds_write2st64_b32 v167, v102, v70 offset0:96 offset1:128
	ds_write_b32 v167, v94 offset:40960
	ds_write2st64_b32 v168, v79, v87 offset0:32 offset1:64
	ds_write2st64_b32 v168, v103, v71 offset0:96 offset1:128
	ds_write_b32 v168, v95 offset:40960
	v_writelane_b32 v1, s64, 0
	v_writelane_b32 v1, s65, 1
	v_writelane_b32 v1, s66, 2
	v_writelane_b32 v1, s67, 3
	v_writelane_b32 v1, s68, 4
	v_writelane_b32 v1, s69, 5
	v_writelane_b32 v1, s70, 6
	v_writelane_b32 v1, s71, 7
	v_lshl_add_u32 v4, v194, 2, v195
	v_add_u32_e32 v4, s49, v4
	v_ashrrev_i32_e32 v5, 31, v4
	v_lshl_add_u64 v[4:5], s[30:31], 0, v[4:5]
	v_lshlrev_b64 v[4:5], 6, v[4:5]
	v_lshl_add_u64 v[4:5], s[34:35], 0, v[4:5]
	s_mov_b64 exec, 0xff
	global_store_dword v[4:5], v1, off
	s_mov_b64 exec, -1
	s_add_i32 s50, s48, 1
	s_cmpk_eq_i32 s48, 0x47
	s_waitcnt lgkmcnt(0)
	s_barrier
	s_cbranch_scc1 .LBB0_1682
	s_lshl_b32 s38, s50, 5
	s_cmp_lt_u32 s48, 7
	s_cselect_b32 s36, 0xff, s44
	s_sub_i32 s39, s36, s38
	s_and_b64 s[36:37], s[28:29], exec
	s_cselect_b32 s36, s38, s39
	v_add_u32_e32 v0, s36, v194
	v_ashrrev_i32_e32 v1, 31, v0
	v_lshl_add_u64 v[0:1], v[0:1], 0, s[24:25]
	v_lshlrev_b64 v[0:1], 8, v[0:1]
	v_lshl_add_u64 v[0:1], v[126:127], 0, v[0:1]
	global_load_dwordx4 v[32:35], v[0:1], off
	global_load_dwordx4 v[36:39], v[0:1], off offset:32
	global_load_dwordx4 v[40:43], v[0:1], off offset:64
	global_load_dwordx4 v[44:47], v[0:1], off offset:96
	v_add_u32_e32 v2, s36, v196
	v_ashrrev_i32_e32 v3, 31, v2
	v_lshl_add_u64 v[2:3], v[2:3], 0, s[24:25]
	v_lshlrev_b64 v[2:3], 11, v[2:3]
	v_lshl_add_u64 v[4:5], v[202:203], 0, v[2:3]
	v_lshl_add_u64 v[6:7], v[204:205], 0, v[2:3]
	v_lshl_add_u64 v[8:9], v[206:207], 0, v[2:3]
	global_load_dwordx4 v[184:187], v[4:5], off
	global_load_dwordx4 v[188:191], v[6:7], off
	global_load_dwordx4 v[198:201], v[8:9], off
